# attention loop: K/V LDS-write addresses kept in registers across the loop (no per-half-step recomputation)
# speedup vs baseline: 1.0107x; 1.0107x over previous
; __device__ __forceinline__ void partialSM(f32x16& p0, f32x16& p1, float& m_reg, float& mn, float& alpha) {
;     float pmax = p0[0]; for (int r = 1; r < 16; ++r) pmax = fmaxf(pmax, p0[r]); for (int r = 0; r < 16; ++r) pmax = fmaxf(pmax, p1[r]);
;     { auto rr = __builtin_amdgcn_permlane32_swap(__float_as_uint(pmax), __float_as_uint(pmax), false, false);
;       pmax = fmaxf(__uint_as_float(rr[0]), __uint_as_float(rr[1])); }
;     constexpr float C2 = 1.4426950408889634f * SCALE;
;     if (__builtin_expect(__all((pmax - m_reg) * SCALE <= THR), 1)) { mn = m_reg; alpha = 1.f; }
;     else { mn = fmaxf(m_reg, pmax); alpha = __builtin_amdgcn_exp2f((m_reg - mn) * C2); m_reg = mn; }
;     const float mnL = -mn * C2;
;     for (int r = 0; r < 16; ++r) p0[r] = fmaf(p0[r], C2, mnL); for (int r = 0; r < 16; ++r) p1[r] = fmaf(p1[r], C2, mnL);
;     for (int r = 0; r < 16; ++r) p0[r] = __builtin_amdgcn_exp2f(p0[r]);
; }
; __device__ __forceinline__ void fox_prime(const BlockRef& cur, char* lds, char* cbcur, Seam& S) {
;     const int tid = threadIdx.x, wid = __builtin_amdgcn_readfirstlane(tid >> 6), lane = tid & 63, r32 = lane & 31, hi = lane >> 5;
;     const int sr = tid >> 4, sc = (tid & 15) * 8; char* K_lds = lds + 2 * SHM_V;
;     for (int d0 = 0; d0 < 8; ++d0) S.qr[d0] = load8(cur.Q + (size_t)(wid * QBLK + r32) * QP + d0 * 16 + hi * 8);
;     SLOAD_H(cur.K, cur.V, cur.P0 + QB - KVBLK); VMW(); SWRITE_HK(0);
;     fill_cb(cur.C, cur.P0, cbcur);
;     __syncthreads();
; }
; __device__ __forceinline__ void fox_block(const BlockRef& cur, const BlockRef& nxt, char* lds, char* cbcur, char* cbnxt, Seam& S) {
;     const int tid = threadIdx.x, wid = __builtin_amdgcn_readfirstlane(tid >> 6), lane = tid & 63, r32 = lane & 31, hi = lane >> 5;
;     const int W = 1 << 30;
;     const int NT = (cur.P0 + QB) / KVBLK;
;     const int qlo = cur.P0 + wid * QBLK, qm = qlo + r32 - 4 * hi;
;     char* V_lds = lds; char* K_lds = lds + 2 * SHM_V;
;     float* ws = (float*)(lds + LDS_WS_OFF) + wid * 64; float* li_l = ws, * al_l = ws + 32;
;     float m_reg = -1e30f, l_reg = 0; f32x16 o[4] = {};
;     const int sr = tid >> 4, sc = (tid & 15) * 8;
;     const int vb0 = (int)(uintptr_t)V_lds + v_rd_base(lane);
;     const bf16* Kh = cur.K; const bf16* Vh = cur.V;
;     const char* cbl = cbcur + 8 * r32;
;     ...
;     constexpr int NQL = 8;
.LBB0_229:
	s_nop 8
	v_max_f32_e32 v50, v19, v19
	v_max_f32_e32 v51, v18, v18
	v_max_f32_e32 v50, v51, v50
	v_max3_f32 v50, v50, v20, v21
	v_max3_f32 v50, v50, v22, v23
	v_max3_f32 v50, v50, v24, v25
	v_max3_f32 v50, v50, v26, v27
	v_max3_f32 v50, v50, v28, v29
	v_max3_f32 v50, v50, v30, v31
	v_max3_f32 v50, v50, v32, v33
	v_max3_f32 v50, v50, v2, v3
	v_max3_f32 v50, v50, v4, v5
	v_max3_f32 v50, v50, v6, v7
	v_max3_f32 v50, v50, v8, v9
	v_max3_f32 v50, v50, v10, v11
	v_max3_f32 v50, v50, v12, v13
	v_max3_f32 v50, v50, v14, v15
	v_max3_f32 v50, v50, v16, v17
	v_mov_b32_e32 v51, v50
	s_nop 1
	v_permlane32_swap_b32_e32 v50, v51
	v_max_f32_e32 v51, v51, v51
	v_max_f32_e32 v50, v50, v50
	v_max_f32_e32 v50, v50, v51
	s_and_b32 s89, s85, 0x3fffffc0
	v_add_f32_e32 v51, 0x7149f2ca, v50
	s_lshl_b32 s89, s89, 2
	v_mul_f32_e32 v51, 0x3db504f3, v51
	v_max_f32_e32 v50, 0xf149f2ca, v50
	s_add_i32 s89, s89, 0
	v_cmp_ge_f32_e32 vcc, s78, v51
	v_sub_f32_e32 v51, 0xf149f2ca, v50
	s_add_i32 s89, s89, 0x10000
	v_mul_f32_e32 v51, 0x3e0293ee, v51
	v_exp_f32_e32 v51, v51
	s_cmp_eq_u64 vcc, exec
	s_cselect_b64 vcc, -1, 0
	v_cndmask_b32_e32 v217, v50, v210, vcc
	v_mul_f32_e32 v50, 0xbe0293ee, v217
	v_cndmask_b32_e64 v187, v51, 1.0, vcc
	v_mov_b32_e32 v51, v50
	v_fmac_f32_e32 v51, 0x3e0293ee, v33
	v_pk_fma_f32 v[126:127], v[2:3], s[16:17], v[50:51] op_sel_hi:[1,0,0]
	v_mov_b32_e32 v2, v0
	s_waitcnt vmcnt(0)
	v_pk_fma_f32 v[124:125], v[4:5], s[16:17], v[50:51] op_sel_hi:[1,0,0]
	v_ashrrev_i32_e32 v3, 4, v2
	v_and_b32_e32 v4, 0xfffff0, v3
	v_lshlrev_b32_e32 v5, 1, v3
	v_pk_fma_f32 v[120:121], v[6:7], s[16:17], v[50:51] op_sel_hi:[1,0,0]
	v_and_or_b32 v4, v5, 8, v4
	v_lshrrev_b32_e32 v5, 1, v3
	v_and_b32_e32 v7, 3, v3
	v_add_u32_e32 v3, 32, v3
	v_and_or_b32 v5, v5, 4, v7
	v_and_b32_e32 v7, 0xfffff0, v3
	v_lshlrev_b32_e32 v3, 1, v3
	v_and_or_b32 v3, v3, 8, v7
	v_lshrrev_b32_e32 v4, 1, v4
	v_bfe_u32 v6, v2, 2, 2
	v_lshrrev_b32_e32 v3, 1, v3
	v_or_b32_e32 v4, v4, v6
	v_lshlrev_b32_e32 v2, 4, v2
	v_or_b32_e32 v3, v3, v6
	v_lshlrev_b32_e32 v4, 9, v4
	v_and_b32_e32 v2, 48, v2
	v_lshlrev_b32_e32 v3, 9, v3
	v_lshl_add_u32 v5, v5, 6, 0
	v_add3_u32 v4, v5, v4, v2
	v_add3_u32 v2, v5, v3, v2
	s_waitcnt vmcnt(3)
	ds_write_b128 v4, v[46:49] offset:16384
	s_waitcnt vmcnt(2)
	ds_write_b128 v2, v[42:45] offset:16384
	v_mov_b32_e32 v2, v0
	v_fmamk_f32 v18, v18, 0x3e0293ee, v50
	v_lshlrev_b32_e32 v3, 4, v2
	v_and_b32_e32 v2, 0x70, v2
	v_and_b32_e32 v4, 0xffffff00, v3
	v_bitop3_b32 v2, v3, v2, s79 bitop3:0x6c
	v_fmamk_f32 v19, v19, 0x3e0293ee, v50
	v_fmamk_f32 v20, v20, 0x3e0293ee, v50
	v_fmamk_f32 v21, v21, 0x3e0293ee, v50
	v_fmamk_f32 v22, v22, 0x3e0293ee, v50
	v_fmamk_f32 v23, v23, 0x3e0293ee, v50
	v_fmamk_f32 v24, v24, 0x3e0293ee, v50
	v_fmamk_f32 v25, v25, 0x3e0293ee, v50
	v_fmamk_f32 v26, v26, 0x3e0293ee, v50
	v_fmamk_f32 v27, v27, 0x3e0293ee, v50
	v_fmamk_f32 v28, v28, 0x3e0293ee, v50
	v_fmamk_f32 v29, v29, 0x3e0293ee, v50
	v_fmamk_f32 v30, v30, 0x3e0293ee, v50
	v_fmamk_f32 v31, v31, 0x3e0293ee, v50
	v_fmamk_f32 v32, v32, 0x3e0293ee, v50
	v_add3_u32 v2, 0, v4, v2
	v_exp_f32_e32 v234, v18
	v_exp_f32_e32 v236, v19
	v_exp_f32_e32 v232, v20
	v_exp_f32_e32 v235, v21
	v_exp_f32_e32 v231, v22
	v_exp_f32_e32 v233, v23
	v_exp_f32_e32 v229, v24
	v_exp_f32_e32 v230, v25
	v_exp_f32_e32 v226, v26
	v_exp_f32_e32 v228, v27
	v_exp_f32_e32 v225, v28
	v_exp_f32_e32 v227, v29
	v_exp_f32_e32 v222, v30
	v_exp_f32_e32 v224, v31
	v_exp_f32_e32 v221, v32
	v_exp_f32_e32 v223, v51
	s_waitcnt vmcnt(1)
	ds_write_b128 v2, v[34:37] offset:49152
	s_waitcnt vmcnt(0)
	ds_write_b128 v2, v[38:41] offset:57344
	v_add_u32_e32 v2, 0xc0, v198
	v_pk_fma_f32 v[118:119], v[16:17], s[16:17], v[50:51] op_sel_hi:[1,0,0]
	v_lshl_add_u64 v[190:191], s[4:5], 0, v[182:183]
	v_add_u32_e32 v2, s76, v2
	s_lshl_b32 s4, s77, 6
	v_mov_b32_e32 v16, v183
	v_mov_b32_e32 v17, v183
	v_pk_fma_f32 v[122:123], v[14:15], s[16:17], v[50:51] op_sel_hi:[1,0,0]
	v_pk_fma_f32 v[128:129], v[12:13], s[16:17], v[50:51] op_sel_hi:[1,0,0]
	v_pk_fma_f32 v[114:115], v[10:11], s[16:17], v[50:51] op_sel_hi:[1,0,0]
	v_pk_fma_f32 v[116:117], v[8:9], s[16:17], v[50:51] op_sel_hi:[1,0,0]
	v_subrev_u32_e32 v216, s4, v2
	v_mov_b32_e32 v2, v183
	v_mov_b32_e32 v3, v183
	v_mov_b32_e32 v4, v183
	v_mov_b32_e32 v5, v183
	v_mov_b32_e32 v6, v183
	v_mov_b32_e32 v7, v183
	v_mov_b32_e32 v8, v183
	v_mov_b32_e32 v9, v183
	v_mov_b32_e32 v10, v183
	v_mov_b32_e32 v11, v183
	v_mov_b32_e32 v12, v183
	v_mov_b32_e32 v13, v183
	v_mov_b32_e32 v14, v183
	v_mov_b32_e32 v15, v183
	v_mov_b64_e32 v[64:65], v[16:17]
	v_mov_b64_e32 v[48:49], v[16:17]
	v_mov_b64_e32 v[32:33], v[16:17]
	s_mov_b32 s85, 2
	v_lshl_add_u64 v[188:189], s[74:75], 0, v[182:183]
	v_lshl_add_u32 v212, v1, 2, s89
	v_lshl_add_u32 v211, v203, 2, s89
	v_lshl_add_u32 v215, s77, 9, v202
	s_add_i32 s89, s4, 0xffffffbf
	v_mov_b32_e32 v214, 0
	v_mov_b64_e32 v[62:63], v[14:15]
	v_mov_b64_e32 v[60:61], v[12:13]
	v_mov_b64_e32 v[58:59], v[10:11]
	v_mov_b64_e32 v[56:57], v[8:9]
	v_mov_b64_e32 v[54:55], v[6:7]
	v_mov_b64_e32 v[52:53], v[4:5]
	v_mov_b64_e32 v[50:51], v[2:3]
	v_mov_b64_e32 v[46:47], v[14:15]
	v_mov_b64_e32 v[44:45], v[12:13]
	v_mov_b64_e32 v[42:43], v[10:11]
	v_mov_b64_e32 v[40:41], v[8:9]
	v_mov_b64_e32 v[38:39], v[6:7]
	v_mov_b64_e32 v[36:37], v[4:5]
	v_mov_b64_e32 v[34:35], v[2:3]
	v_mov_b64_e32 v[30:31], v[14:15]
	v_mov_b64_e32 v[28:29], v[12:13]
	v_mov_b64_e32 v[26:27], v[10:11]
	v_mov_b64_e32 v[24:25], v[8:9]
	v_mov_b64_e32 v[22:23], v[6:7]
	v_mov_b64_e32 v[20:21], v[4:5]
	v_mov_b64_e32 v[18:19], v[2:3]
	v_and_b32_e32 v239, 0x70, v0
	v_and_b32_e32 v201, 0xffffff00, v184
	v_and_b32_e32 v1, 0xf0, v184
	v_xor_b32_e32 v1, v1, v239
	v_add_u32_e32 v201, v201, v1
	v_bfe_u32 v1, v0, 6, 1
	v_lshlrev_b32_e32 v1, 11, v1
	v_bfe_u32 v239, v0, 8, 1
	v_lshl_or_b32 v1, v239, 12, v1
	v_bfe_u32 v239, v0, 2, 2
	v_lshl_or_b32 v1, v239, 9, v1
	v_bfe_u32 v239, v0, 4, 2
	v_lshl_or_b32 v1, v239, 6, v1
	v_bfe_u32 v239, v0, 7, 1
	v_lshl_or_b32 v1, v239, 8, v1
	v_and_b32_e32 v239, 3, v0
	v_lshl_or_b32 v1, v239, 4, v1
	v_lshlrev_b32_e32 v239, 2, v0
	s_waitcnt lgkmcnt(0)
	s_barrier

; #define SBAR() __builtin_amdgcn_sched_barrier(0)
; #define VMW() asm volatile("s_waitcnt vmcnt(0)" ::: "memory")
; #define SLOAD_H(Kp, Vp, k0) do { S.st_v0 = load8(ROWK(Vp, k0, sr)); S.st_v1 = load8(ROWK(Vp, k0, 32 + sr));              \
;                          S.st_k0 = load8(ROWK(Kp, k0, sr)); S.st_k1 = load8(ROWK(Kp, k0, 32 + sr)); } while (0)
; #define SWRITE_HV(bf) do { OPQ_TID(); const int vst0_ = v_st(sr_, sc_), vst1_ = v_st(32 + sr_, sc_); *(bf16x8*)(V_lds + (bf) * SHM_V + vst0_) = S.st_v0; *(bf16x8*)(V_lds + (bf) * SHM_V + vst1_) = S.st_v1; } while (0)
; #define SWRITE_H(bf) do { SWRITE_HV(bf); SWRITE_HK(bf); } while (0)
; #define MASKT(P0_, P1_, t) do { const int kb_ = KBASE(t); if (kb_ + KVBLK - 1 > qlo) mask_tile(P0_, P1_, qm - kb_, (unsigned)W); } while (0)
; __device__ __forceinline__ void partialSM(f32x16& p0, f32x16& p1, float& m_reg, float& mn, float& alpha) {
;     float pmax = p0[0]; for (int r = 1; r < 16; ++r) pmax = fmaxf(pmax, p0[r]); for (int r = 0; r < 16; ++r) pmax = fmaxf(pmax, p1[r]);
;     { auto rr = __builtin_amdgcn_permlane32_swap(__float_as_uint(pmax), __float_as_uint(pmax), false, false);
;       pmax = fmaxf(__uint_as_float(rr[0]), __uint_as_float(rr[1])); }
;     constexpr float C2 = 1.4426950408889634f * SCALE;
;     if (__builtin_expect(__all((pmax - m_reg) * SCALE <= THR), 1)) { mn = m_reg; alpha = 1.f; }
;     else { mn = fmaxf(m_reg, pmax); alpha = __builtin_amdgcn_exp2f((m_reg - mn) * C2); m_reg = mn; }
; __device__ __forceinline__ void fox_block(const BlockRef& cur, const BlockRef& nxt, char* lds, char* cbcur, char* cbnxt, Seam& S) {
;     ...
;     constexpr int NQL = 8;
;     ...
;     f32x16 pA0, pA1, pB0, pB1; float mnA, mnB, alA, alB; bf16x8 pa0, pa1, pa2, pa3;
;     SWRITE_HV(0); SBAR();
;     if (NT > 1) { SLOAD_H(Kh, Vh, KBASE(1)); }
;     SBAR(); qkt<0>(pA0, pA1, K_lds, cbl + 8 * KBASE(0), r32, hi, S.qr);
;     MASKT(pA0, pA1, 0); partialSM(pA0, pA1, m_reg, mnA, alA);
;     if (NT > 1) { VMW(); SWRITE_H(1); }
;     __syncthreads();
.LBB0_232:
	v_max_f32_e32 v66, v87, v87
	v_max_f32_e32 v67, v86, v86
	v_max_f32_e32 v66, v67, v66
	v_max3_f32 v66, v66, v88, v89
	v_max3_f32 v66, v66, v90, v91
	v_max3_f32 v66, v66, v92, v93
	v_max3_f32 v66, v66, v94, v95
	v_max3_f32 v66, v66, v96, v97
	v_max3_f32 v66, v66, v98, v99
	v_max3_f32 v66, v66, v100, v101
	v_max3_f32 v66, v66, v70, v71
	v_max3_f32 v66, v66, v72, v73
	v_max3_f32 v66, v66, v74, v75
	v_max3_f32 v66, v66, v76, v77
	v_max3_f32 v66, v66, v78, v79
	v_max3_f32 v66, v66, v80, v81
	v_max3_f32 v66, v66, v82, v83
	v_max3_f32 v66, v66, v84, v85
	v_mov_b32_e32 v67, v66
	s_nop 1
	v_permlane32_swap_b32_e32 v66, v67
	v_max_f32_e32 v67, v67, v67
	v_max_f32_e32 v66, v66, v66
	v_max_f32_e32 v66, v66, v67
	v_max_f32_e32 v68, v217, v217
	v_sub_f32_e32 v67, v66, v217
	v_max_f32_e32 v66, v68, v66
	v_sub_f32_e32 v68, v217, v66
	v_mul_f32_e32 v68, 0x3e0293ee, v68
	v_mul_f32_e32 v67, 0x3db504f3, v67
	v_exp_f32_e32 v68, v68
	v_cmp_ge_f32_e32 vcc, s78, v67
	s_cmp_eq_u64 vcc, exec
	s_cselect_b64 s[4:5], -1, 0
	v_cndmask_b32_e64 v220, v68, 1.0, s[4:5]
	s_barrier
	s_waitcnt vmcnt(0)
	v_cmp_gt_f32_e32 vcc, 1.0, v220
	s_waitcnt vmcnt(3)
	ds_write_b128 v1, v[174:177] offset:0
	s_waitcnt vmcnt(2)
	ds_write_b128 v1, v[170:173] offset:8192
	s_waitcnt vmcnt(1)
	ds_write_b128 v201, v[166:169] offset:32768
	s_waitcnt vmcnt(0)
	ds_write_b128 v201, v[178:181] offset:40960
	s_cbranch_vccz .LBB0_236
	s_and_saveexec_b64 s[74:75], s[6:7]
	ds_write_b32 v212, v220 offset:128
	s_or_b64 exec, exec, s[74:75]
	s_waitcnt lgkmcnt(0)
	ds_read_b128 v[104:107], v211 offset:224
	ds_read_b128 v[108:111], v211 offset:192
	ds_read_b128 v[112:115], v211 offset:160
	ds_read_b128 v[116:119], v211 offset:128
	s_waitcnt lgkmcnt(3)
	v_pk_mul_f32 v[16:17], v[16:17], v[106:107]
	s_waitcnt lgkmcnt(2)
	v_pk_mul_f32 v[12:13], v[12:13], v[110:111]
	s_waitcnt lgkmcnt(1)
	v_pk_mul_f32 v[8:9], v[8:9], v[114:115]
	s_waitcnt lgkmcnt(0)
	v_pk_mul_f32 v[4:5], v[4:5], v[118:119]
	v_pk_mul_f32 v[14:15], v[14:15], v[104:105]
	v_pk_mul_f32 v[10:11], v[10:11], v[108:109]
	v_pk_mul_f32 v[6:7], v[6:7], v[112:113]
	v_pk_mul_f32 v[2:3], v[2:3], v[116:117]
	v_pk_mul_f32 v[64:65], v[64:65], v[106:107]
	v_pk_mul_f32 v[60:61], v[60:61], v[110:111]
	v_pk_mul_f32 v[56:57], v[56:57], v[114:115]
	v_pk_mul_f32 v[52:53], v[52:53], v[118:119]
	v_pk_mul_f32 v[62:63], v[62:63], v[104:105]
	v_pk_mul_f32 v[58:59], v[58:59], v[108:109]
	v_pk_mul_f32 v[54:55], v[54:55], v[112:113]
	v_pk_mul_f32 v[50:51], v[50:51], v[116:117]
	v_pk_mul_f32 v[48:49], v[48:49], v[106:107]
	v_pk_mul_f32 v[44:45], v[44:45], v[110:111]
	v_pk_mul_f32 v[40:41], v[40:41], v[114:115]
	v_pk_mul_f32 v[36:37], v[36:37], v[118:119]
	v_pk_mul_f32 v[46:47], v[46:47], v[104:105]
	v_pk_mul_f32 v[42:43], v[42:43], v[108:109]
	v_pk_mul_f32 v[38:39], v[38:39], v[112:113]
	v_pk_mul_f32 v[34:35], v[34:35], v[116:117]
	v_pk_mul_f32 v[32:33], v[32:33], v[106:107]
	v_pk_mul_f32 v[28:29], v[28:29], v[110:111]
	v_pk_mul_f32 v[24:25], v[24:25], v[114:115]
	v_pk_mul_f32 v[20:21], v[20:21], v[118:119]
	v_pk_mul_f32 v[30:31], v[30:31], v[104:105]
	v_pk_mul_f32 v[26:27], v[26:27], v[108:109]
	v_pk_mul_f32 v[22:23], v[22:23], v[112:113]
	v_pk_mul_f32 v[18:19], v[18:19], v[116:117]

; __device__ __forceinline__ void partialSM(f32x16& p0, f32x16& p1, float& m_reg, float& mn, float& alpha) {
;     float pmax = p0[0]; for (int r = 1; r < 16; ++r) pmax = fmaxf(pmax, p0[r]); for (int r = 0; r < 16; ++r) pmax = fmaxf(pmax, p1[r]);
;     { auto rr = __builtin_amdgcn_permlane32_swap(__float_as_uint(pmax), __float_as_uint(pmax), false, false);
;       pmax = fmaxf(__uint_as_float(rr[0]), __uint_as_float(rr[1])); }
;     constexpr float C2 = 1.4426950408889634f * SCALE;
;     if (__builtin_expect(__all((pmax - m_reg) * SCALE <= THR), 1)) { mn = m_reg; alpha = 1.f; }
;     else { mn = fmaxf(m_reg, pmax); alpha = __builtin_amdgcn_exp2f((m_reg - mn) * C2); m_reg = mn; }
.LBB0_240:
	v_max_f32_e32 v194, v115, v115
	v_max_f32_e32 v195, v114, v114
	v_max_f32_e32 v194, v195, v194
	v_max3_f32 v194, v194, v116, v117
	v_max3_f32 v194, v194, v118, v119
	v_max3_f32 v194, v194, v120, v121
	v_max3_f32 v194, v194, v122, v123
	v_max3_f32 v194, v194, v124, v125
	v_max3_f32 v194, v194, v126, v127
	v_max3_f32 v194, v194, v128, v129
	v_max3_f32 v194, v194, v98, v99
	v_max3_f32 v194, v194, v100, v101
	v_max3_f32 v194, v194, v102, v103
	v_max3_f32 v194, v194, v104, v105
	v_max3_f32 v194, v194, v106, v107
	v_max3_f32 v194, v194, v108, v109
	v_max3_f32 v194, v194, v110, v111
	v_max3_f32 v194, v194, v112, v113
	v_mov_b32_e32 v195, v194
	s_nop 1
	v_permlane32_swap_b32_e32 v194, v195
	v_max_f32_e32 v195, v195, v195
	v_max_f32_e32 v194, v194, v194
	v_max_f32_e32 v221, v194, v195
	v_sub_f32_e32 v194, v221, v217
	v_mul_f32_e32 v194, 0x3db504f3, v194
	v_cmp_ge_f32_e32 vcc, s78, v194
	s_cmp_eq_u64 vcc, exec
	s_cselect_b64 s[4:5], -1, 0
	s_andn2_b64 vcc, exec, s[74:75]
	s_barrier
	s_cbranch_vccnz .LBB0_242
	s_waitcnt vmcnt(0)
	s_waitcnt vmcnt(3)
	ds_write_b128 v1, v[174:177] offset:16384
	s_waitcnt vmcnt(2)
	ds_write_b128 v1, v[170:173] offset:24576
	s_waitcnt vmcnt(1)
	ds_write_b128 v201, v[166:169] offset:49152
	s_waitcnt vmcnt(0)
	ds_write_b128 v201, v[178:181] offset:57344

; #define SBAR() __builtin_amdgcn_sched_barrier(0)
; template <int KB>
; __device__ __forceinline__ void qkt(f32x16& p0, f32x16& p1, const char* K_lds, const char* cbt, int r32, int hi, const bf16x8* qr) {
;     { const u32x2 e0 = *(const u32x2*)(cbt), e1 = *(const u32x2*)(cbt + 32 * 8);
;       const unsigned c0 = hi ? 0u : 0x3F803F80u, c1 = hi ? 0u : 0x00003F80u;
;       const u32x4 k0 = {e0.x, e0.y, e0.x, e0.y}, k1 = {e1.x, e1.y, e1.x, e1.y}, q1 = {c0, c1, 0u, 0u};
;       p0 = __builtin_amdgcn_mfma_f32_32x32x16_bf16(__builtin_bit_cast(bf16x8, k0), __builtin_bit_cast(bf16x8, q1), f32x16{}, 0, 0, 0);
;       p1 = __builtin_amdgcn_mfma_f32_32x32x16_bf16(__builtin_bit_cast(bf16x8, k1), __builtin_bit_cast(bf16x8, q1), f32x16{}, 0, 0, 0); }
;     const char* kb[4];
; #pragma unroll
;     for (int dd = 0; dd < 4; ++dd) kb[dd] = K_lds + KB * SHM_K + KSWZ(r32, (dd * 16 + hi * 8) * 2);
; #pragma unroll
;     for (int d0 = 0; d0 < 8; ++d0) { const char* a = kb[d0 & 3] + (d0 >> 2) * 128;
;         bf16x8 b0 = *reinterpret_cast<const bf16x8*>(a);
;         bf16x8 b1 = *reinterpret_cast<const bf16x8*>(a + 32 * 256);
;         p0 = __builtin_amdgcn_mfma_f32_32x32x16_bf16(b0, qr[d0], p0, 0, 0, 0);
;         p1 = __builtin_amdgcn_mfma_f32_32x32x16_bf16(b1, qr[d0], p1, 0, 0, 0); }
; }
; __device__ __forceinline__ void fox_block(const BlockRef& cur, const BlockRef& nxt, char* lds, char* cbcur, char* cbnxt, Seam& S) {
;     ...
;     const bool even = (NT & 1) == 0;
;     if (even) { SBAR(); qkt<1>(pB0, pB1, K_lds, cbl + 8 * KBASE(NT - 1), r32, hi, S.qr); SBAR(); }
.LBB0_248:
	v_and_b32_e32 v1, 31, v0
	v_and_b32_e32 v201, 63, v0
	s_bitcmp0_b32 s84, 6
	s_cselect_b64 s[4:5], -1, 0
	s_and_b64 vcc, exec, s[4:5]
	s_cbranch_vccz .LBB0_250
	ds_read2_b64 v[82:85], v200 offset1:32
	ds_read_b128 v[98:101], v205 offset:49152
	ds_read_b128 v[102:105], v205 offset:49280
	s_waitcnt lgkmcnt(2)
	v_mov_b32_e32 v66, v82
	v_mov_b32_e32 v67, v83
	v_mov_b32_e32 v68, v82
	v_mov_b32_e32 v69, v83
	v_mov_b32_e32 v82, v84
	v_mov_b32_e32 v83, v85
	v_mfma_f32_32x32x16_bf16 v[66:81], v[66:69], v[162:165], 0
	s_nop 0
	v_mfma_f32_32x32x16_bf16 v[82:97], v[82:85], v[162:165], 0
	s_waitcnt lgkmcnt(1)
	v_mfma_f32_32x32x16_bf16 v[66:81], v[98:101], v[158:161], v[66:81]
	ds_read_b128 v[98:101], v205 offset:57344
	ds_read_b128 v[106:109], v205 offset:57472
	s_waitcnt lgkmcnt(1)
	v_mfma_f32_32x32x16_bf16 v[82:97], v[98:101], v[158:161], v[82:97]
	ds_read_b128 v[98:101], v206 offset:49152
	ds_read_b128 v[110:113], v206 offset:49280
	s_waitcnt lgkmcnt(1)
	v_mfma_f32_32x32x16_bf16 v[66:81], v[98:101], v[154:157], v[66:81]
	ds_read_b128 v[98:101], v206 offset:57344
	ds_read_b128 v[158:161], v206 offset:57472
	s_waitcnt lgkmcnt(1)
	v_mfma_f32_32x32x16_bf16 v[82:97], v[98:101], v[154:157], v[82:97]
	ds_read_b128 v[98:101], v207 offset:49152
	ds_read_b128 v[154:157], v207 offset:49280
	s_waitcnt lgkmcnt(1)
	v_mfma_f32_32x32x16_bf16 v[66:81], v[98:101], v[150:153], v[66:81]
	ds_read_b128 v[98:101], v207 offset:57344
	ds_read_b128 v[168:171], v207 offset:57472
	s_waitcnt lgkmcnt(1)
	v_mfma_f32_32x32x16_bf16 v[82:97], v[98:101], v[150:153], v[82:97]
	ds_read_b128 v[98:101], v208 offset:49152
	ds_read_b128 v[150:153], v208 offset:49280
	s_waitcnt lgkmcnt(1)
	v_mfma_f32_32x32x16_bf16 v[66:81], v[98:101], v[146:149], v[66:81]
	ds_read_b128 v[98:101], v208 offset:57344
	ds_read_b128 v[172:175], v208 offset:57472
	s_waitcnt lgkmcnt(1)
	v_mfma_f32_32x32x16_bf16 v[82:97], v[98:101], v[146:149], v[82:97]
	v_mfma_f32_32x32x16_bf16 v[66:81], v[102:105], v[142:145], v[66:81]
	v_mfma_f32_32x32x16_bf16 v[82:97], v[106:109], v[142:145], v[82:97]
	v_mfma_f32_32x32x16_bf16 v[66:81], v[110:113], v[138:141], v[66:81]
	v_mfma_f32_32x32x16_bf16 v[82:97], v[158:161], v[138:141], v[82:97]
	v_mfma_f32_32x32x16_bf16 v[66:81], v[154:157], v[134:137], v[66:81]
	v_mfma_f32_32x32x16_bf16 v[82:97], v[168:171], v[134:137], v[82:97]
	v_mfma_f32_32x32x16_bf16 v[66:81], v[150:153], v[130:133], v[66:81]
	s_waitcnt lgkmcnt(0)
	v_mfma_f32_32x32x16_bf16 v[82:97], v[172:175], v[130:133], v[82:97]
